# counted-wait placement in the sample conv tile (early full wait after the first weight load removed) plus phase-0 section swap, on the full stack
# baseline (speedup 1.0000x reference)
.LBB0_519:
	v_cndmask_b32_e64 v2, 0, 1, s[92:93]
	v_add_u32_e32 v18, s4, v0
	v_cmp_ne_u32_e64 s[6:7], 1, v2
	v_lshlrev_b64 v[2:3], 2, v[18:19]
	v_lshl_add_u64 v[4:5], s[90:91], 0, v[2:3]
	v_add_co_u32_e32 v6, vcc, 0x1000, v4
	global_load_dword v24, v[4:5], off
	global_load_dword v61, v[4:5], off offset:2048
	v_addc_co_u32_e32 v7, vcc, 0, v5, vcc
	global_load_dword v60, v[6:7], off
	global_load_dword v58, v[6:7], off offset:2048
	v_add_co_u32_e32 v6, vcc, 0x2000, v4
	s_mov_b32 s5, 0xf000
	s_nop 0
	v_addc_co_u32_e32 v7, vcc, 0, v5, vcc
	global_load_dword v57, v[6:7], off
	global_load_dword v54, v[6:7], off offset:2048
	v_add_co_u32_e32 v6, vcc, 0x3000, v4
	s_nop 1
	v_addc_co_u32_e32 v7, vcc, 0, v5, vcc
	global_load_dword v56, v[6:7], off
	global_load_dword v52, v[6:7], off offset:2048
	v_add_co_u32_e32 v6, vcc, s0, v4
	s_nop 1
	v_addc_co_u32_e32 v7, vcc, 0, v5, vcc
	global_load_dword v51, v[6:7], off
	global_load_dword v50, v[6:7], off offset:2048
	v_add_co_u32_e32 v6, vcc, 0x5000, v4
	s_nop 1
	v_addc_co_u32_e32 v7, vcc, 0, v5, vcc
	global_load_dword v49, v[6:7], off
	global_load_dword v48, v[6:7], off offset:2048
	v_add_co_u32_e32 v6, vcc, 0x6000, v4
	s_nop 1
	v_addc_co_u32_e32 v7, vcc, 0, v5, vcc
	global_load_dword v47, v[6:7], off
	global_load_dword v45, v[6:7], off offset:2048
	v_add_co_u32_e32 v6, vcc, 0x7000, v4
	s_nop 1
	v_addc_co_u32_e32 v7, vcc, 0, v5, vcc
	global_load_dword v46, v[6:7], off
	global_load_dword v44, v[6:7], off offset:2048
	v_add_co_u32_e32 v6, vcc, 0x8000, v4
	s_nop 1
	v_addc_co_u32_e32 v7, vcc, 0, v5, vcc
	global_load_dword v43, v[6:7], off
	global_load_dword v42, v[6:7], off offset:2048
	v_add_co_u32_e32 v6, vcc, 0x9000, v4
	s_nop 1
	v_addc_co_u32_e32 v7, vcc, 0, v5, vcc
	global_load_dword v41, v[6:7], off
	global_load_dword v40, v[6:7], off offset:2048
	v_add_co_u32_e32 v6, vcc, 0xa000, v4
	s_nop 1
	v_addc_co_u32_e32 v7, vcc, 0, v5, vcc
	global_load_dword v39, v[6:7], off
	global_load_dword v26, v[6:7], off offset:2048
	v_add_co_u32_e32 v6, vcc, 0xb000, v4
	s_nop 1
	v_addc_co_u32_e32 v7, vcc, 0, v5, vcc
	global_load_dword v27, v[6:7], off
	global_load_dword v25, v[6:7], off offset:2048
	v_add_co_u32_e32 v6, vcc, 0xc000, v4
	s_nop 1
	v_addc_co_u32_e32 v7, vcc, 0, v5, vcc
	global_load_dword v23, v[6:7], off
	global_load_dword v14, v[6:7], off offset:2048
	v_add_co_u32_e32 v6, vcc, 0xd000, v4
	s_nop 1
	v_addc_co_u32_e32 v7, vcc, 0, v5, vcc
	global_load_dword v10, v[6:7], off
	global_load_dword v9, v[6:7], off offset:2048
	v_add_co_u32_e32 v6, vcc, s1, v4
	s_nop 1
	v_addc_co_u32_e32 v7, vcc, 0, v5, vcc
	v_add_co_u32_e32 v4, vcc, s5, v4
	global_load_dword v8, v[6:7], off
	s_nop 0
	global_load_dword v7, v[6:7], off offset:2048
	v_addc_co_u32_e32 v5, vcc, 0, v5, vcc
	global_load_dword v6, v[4:5], off
	v_lshl_add_u64 v[4:5], s[86:87], 0, v[2:3]
	s_movk_i32 s5, 0x1000
	v_add_co_u32_e32 v12, vcc, s5, v4
	s_movk_i32 s5, 0x2000
	s_nop 0
	v_addc_co_u32_e32 v13, vcc, 0, v5, vcc
	v_add_co_u32_e32 v16, vcc, s5, v4
	s_movk_i32 s5, 0x3000
	s_nop 0
	v_addc_co_u32_e32 v17, vcc, 0, v5, vcc
	global_load_dword v11, v[4:5], off
	global_load_dword v15, v[4:5], off offset:2048
	global_load_dword v65, v[16:17], off offset:-4096
	global_load_dword v66, v[12:13], off offset:2048
	global_load_dword v67, v[16:17], off
	global_load_dword v68, v[16:17], off offset:2048
	v_add_co_u32_e32 v12, vcc, s5, v4
	s_movk_i32 s5, 0x5000
	s_nop 0
	v_addc_co_u32_e32 v13, vcc, 0, v5, vcc
	v_add_co_u32_e32 v16, vcc, s0, v4
	s_waitcnt vmcnt(0) lgkmcnt(0)
	v_fma_f32 v11, v24, v11, 0
	v_addc_co_u32_e32 v17, vcc, 0, v5, vcc
	global_load_dword v69, v[16:17], off offset:-4096
	global_load_dword v70, v[12:13], off offset:2048
	global_load_dword v71, v[16:17], off
	global_load_dword v72, v[16:17], off offset:2048
	v_add_co_u32_e32 v12, vcc, s5, v4
	s_movk_i32 s5, 0x6000
	s_nop 0
	v_addc_co_u32_e32 v13, vcc, 0, v5, vcc
	v_add_co_u32_e32 v16, vcc, s5, v4
	s_movk_i32 s5, 0x7000
	s_nop 0
	v_addc_co_u32_e32 v17, vcc, 0, v5, vcc
	global_load_dword v73, v[16:17], off offset:-4096
	global_load_dword v74, v[12:13], off offset:2048
	global_load_dword v75, v[16:17], off
	global_load_dword v76, v[16:17], off offset:2048
	v_add_co_u32_e32 v12, vcc, s5, v4
	s_mov_b32 s5, 0x8000
	s_nop 0
	v_addc_co_u32_e32 v13, vcc, 0, v5, vcc
	v_add_co_u32_e32 v16, vcc, s5, v4
	s_mov_b32 s5, 0x9000
	s_nop 0
	v_addc_co_u32_e32 v17, vcc, 0, v5, vcc
	global_load_dword v77, v[16:17], off offset:-4096
	global_load_dword v78, v[12:13], off offset:2048
	global_load_dword v79, v[16:17], off
	global_load_dword v80, v[16:17], off offset:2048
	v_add_co_u32_e32 v12, vcc, s5, v4
	s_mov_b32 s5, 0xa000
	s_nop 0
	v_addc_co_u32_e32 v13, vcc, 0, v5, vcc
	v_add_co_u32_e32 v16, vcc, s5, v4
	s_mov_b32 s5, 0xb000
	s_nop 0
	v_addc_co_u32_e32 v17, vcc, 0, v5, vcc
	global_load_dword v81, v[16:17], off offset:-4096
	global_load_dword v82, v[12:13], off offset:2048
	global_load_dword v83, v[16:17], off
	global_load_dword v84, v[16:17], off offset:2048
	v_add_co_u32_e32 v12, vcc, s5, v4
	s_mov_b32 s5, 0xc000
	s_nop 0
	v_addc_co_u32_e32 v13, vcc, 0, v5, vcc
	v_add_co_u32_e32 v16, vcc, s5, v4
	s_mov_b32 s5, 0xd000
	s_nop 0
	v_addc_co_u32_e32 v17, vcc, 0, v5, vcc
	global_load_dword v85, v[16:17], off offset:-4096
	global_load_dword v86, v[12:13], off offset:2048
	global_load_dword v87, v[16:17], off
	global_load_dword v88, v[16:17], off offset:2048
	v_add_co_u32_e32 v12, vcc, s5, v4
	v_fmac_f32_e32 v11, v61, v15
	s_nop 0
	v_addc_co_u32_e32 v13, vcc, 0, v5, vcc
	v_add_co_u32_e32 v4, vcc, s1, v4
	v_fmac_f32_e32 v11, v60, v65
	s_nop 0
	v_addc_co_u32_e32 v5, vcc, 0, v5, vcc
	global_load_dword v89, v[4:5], off offset:-4096
	global_load_dword v90, v[12:13], off offset:2048
	global_load_dword v64, v[4:5], off
	global_load_dword v62, v[4:5], off offset:2048
	v_lshlrev_b64 v[4:5], 1, v[18:19]
	v_lshl_add_u64 v[12:13], s[68:69], 0, v[4:5]
	global_load_ushort v63, v[12:13], off
	global_load_ushort v59, v[12:13], off offset:1024
	v_lshl_add_u64 v[12:13], s[72:73], 0, v[4:5]
	global_load_ushort v55, v[12:13], off
	global_load_ushort v53, v[12:13], off offset:1024
	v_fma_f32 v12, v24, v15, 0
	v_fmac_f32_e32 v12, v61, v65
	v_fma_f32 v13, v24, v65, 0
	v_fmac_f32_e32 v11, v58, v66
	v_fmac_f32_e32 v12, v60, v66
	v_fmac_f32_e32 v13, v61, v66
	v_fma_f32 v15, v24, v66, 0
	v_fmac_f32_e32 v11, v57, v67
	v_fmac_f32_e32 v12, v58, v67
	v_fmac_f32_e32 v13, v60, v67
	v_fmac_f32_e32 v15, v61, v67
	v_fma_f32 v16, v24, v67, 0
	v_fmac_f32_e32 v11, v54, v68
	v_fmac_f32_e32 v12, v57, v68
	v_fmac_f32_e32 v13, v58, v68
	v_fmac_f32_e32 v15, v60, v68
	v_fmac_f32_e32 v16, v61, v68
	v_fma_f32 v17, v24, v68, 0
	s_waitcnt vmcnt(27)
	v_fmac_f32_e32 v11, v56, v69
	v_fmac_f32_e32 v12, v54, v69
	v_fmac_f32_e32 v13, v57, v69
	v_fmac_f32_e32 v15, v58, v69
	v_fmac_f32_e32 v16, v60, v69
	v_fmac_f32_e32 v17, v61, v69
	v_fma_f32 v18, v24, v69, 0
	s_waitcnt vmcnt(26)
	v_fmac_f32_e32 v11, v52, v70
	v_fmac_f32_e32 v12, v56, v70
	v_fmac_f32_e32 v13, v54, v70
	v_fmac_f32_e32 v15, v57, v70
	v_fmac_f32_e32 v16, v58, v70
	v_fmac_f32_e32 v17, v60, v70
	v_fmac_f32_e32 v18, v61, v70
	v_fma_f32 v24, v24, v70, 0
	s_waitcnt vmcnt(25)
	v_fmac_f32_e32 v11, v51, v71
	v_fmac_f32_e32 v12, v52, v71
	v_fmac_f32_e32 v13, v56, v71
	v_fmac_f32_e32 v15, v54, v71
	v_fmac_f32_e32 v16, v57, v71
	v_fmac_f32_e32 v17, v58, v71
	v_fmac_f32_e32 v18, v60, v71
	v_fmac_f32_e32 v24, v61, v71
	s_waitcnt vmcnt(24)
	v_fmac_f32_e32 v11, v50, v72
	v_fmac_f32_e32 v12, v51, v72
	v_fmac_f32_e32 v13, v52, v72
	v_fmac_f32_e32 v15, v56, v72
	v_fmac_f32_e32 v16, v54, v72
	v_fmac_f32_e32 v17, v57, v72
	v_fmac_f32_e32 v18, v58, v72
	v_fmac_f32_e32 v24, v60, v72
	s_waitcnt vmcnt(23)
	v_fmac_f32_e32 v11, v49, v73
	v_fmac_f32_e32 v12, v50, v73
	v_fmac_f32_e32 v13, v51, v73
	v_fmac_f32_e32 v15, v52, v73
	v_fmac_f32_e32 v16, v56, v73
	v_fmac_f32_e32 v17, v54, v73
	v_fmac_f32_e32 v18, v57, v73
	v_fmac_f32_e32 v24, v58, v73
	v_lshl_add_u64 v[60:61], s[24:25], 0, v[2:3]
	s_waitcnt vmcnt(22)
	v_fmac_f32_e32 v11, v48, v74
	v_fmac_f32_e32 v12, v49, v74
	v_fmac_f32_e32 v13, v50, v74
	v_fmac_f32_e32 v15, v51, v74
	v_fmac_f32_e32 v16, v52, v74
	v_fmac_f32_e32 v17, v56, v74
	v_fmac_f32_e32 v18, v54, v74
	v_fmac_f32_e32 v24, v57, v74
	global_store_dword v[60:61], v73, off
	v_lshl_add_u64 v[60:61], s[26:27], 0, v[2:3]
	s_waitcnt vmcnt(22)
	v_fmac_f32_e32 v11, v47, v75
	v_fmac_f32_e32 v12, v48, v75
	v_fmac_f32_e32 v13, v49, v75
	v_fmac_f32_e32 v15, v50, v75
	v_fmac_f32_e32 v16, v51, v75
	v_fmac_f32_e32 v17, v52, v75
	v_fmac_f32_e32 v18, v56, v75
	v_fmac_f32_e32 v24, v54, v75
	v_lshl_add_u64 v[66:67], s[20:21], 0, v[2:3]
	global_store_dword v[60:61], v74, off
	v_lshl_add_u64 v[60:61], s[28:29], 0, v[2:3]
	s_waitcnt vmcnt(22)
	v_fmac_f32_e32 v11, v45, v76
	v_fmac_f32_e32 v12, v47, v76
	v_fmac_f32_e32 v13, v48, v76
	v_fmac_f32_e32 v15, v49, v76
	v_fmac_f32_e32 v16, v50, v76
	v_fmac_f32_e32 v17, v51, v76
	v_fmac_f32_e32 v18, v52, v76
	v_fmac_f32_e32 v24, v56, v76
	v_lshl_add_u64 v[56:57], s[34:35], 0, v[2:3]
	global_store_dword v[66:67], v71, off
	v_lshl_add_u64 v[66:67], s[22:23], 0, v[2:3]
	global_store_dword v[60:61], v75, off
	v_lshl_add_u64 v[60:61], s[30:31], 0, v[2:3]
	s_waitcnt vmcnt(23)
	global_store_dword v[56:57], v77, off
	v_fmac_f32_e32 v11, v46, v77
	v_fmac_f32_e32 v12, v45, v77
	v_fmac_f32_e32 v13, v47, v77
	v_fmac_f32_e32 v15, v48, v77
	v_fmac_f32_e32 v16, v49, v77
	v_fmac_f32_e32 v17, v50, v77
	v_fmac_f32_e32 v18, v51, v77
	v_fmac_f32_e32 v24, v52, v77
	v_lshl_add_u64 v[56:57], s[36:37], 0, v[2:3]
	global_store_dword v[66:67], v72, off
	global_store_dword v[60:61], v76, off
	s_waitcnt vmcnt(25)
	global_store_dword v[56:57], v78, off
	v_fmac_f32_e32 v11, v44, v78
	v_fmac_f32_e32 v12, v46, v78
	v_fmac_f32_e32 v13, v45, v78
	v_fmac_f32_e32 v15, v47, v78
	v_fmac_f32_e32 v16, v48, v78
	v_fmac_f32_e32 v17, v49, v78
	v_fmac_f32_e32 v18, v50, v78
	v_fmac_f32_e32 v24, v51, v78
	v_lshl_add_u64 v[56:57], s[94:95], 0, v[4:5]
	global_load_ushort v65, v[56:57], off
	global_load_ushort v66, v[56:57], off offset:1024
	v_lshl_add_u64 v[56:57], s[96:97], 0, v[4:5]
	global_load_ushort v67, v[56:57], off
	global_load_ushort v68, v[56:57], off offset:1024
	v_lshl_add_u64 v[56:57], s[2:3], 0, v[4:5]
	v_lshl_add_u64 v[60:61], s[12:13], 0, v[4:5]
	global_load_ushort v58, v[56:57], off
	s_nop 0
	global_load_ushort v57, v[56:57], off offset:1024
	s_nop 0
	global_load_ushort v56, v[60:61], off
	global_load_ushort v54, v[60:61], off offset:1024
	v_lshl_add_u64 v[60:61], s[16:17], 0, v[4:5]
	global_load_ushort v52, v[60:61], off
	global_load_ushort v51, v[60:61], off offset:1024
	v_lshl_add_u64 v[60:61], s[18:19], 0, v[4:5]
	global_load_ushort v5, v[60:61], off
	global_load_ushort v4, v[60:61], off offset:1024
	s_waitcnt vmcnt(37)
	v_fmac_f32_e32 v24, v50, v79
	v_fmac_f32_e32 v18, v49, v79
	s_waitcnt vmcnt(36)
	v_fmac_f32_e32 v24, v49, v80
	v_fmac_f32_e32 v17, v48, v79
	v_fmac_f32_e32 v18, v48, v80
	s_waitcnt vmcnt(35)
	v_fmac_f32_e32 v24, v48, v81
	v_fmac_f32_e32 v16, v47, v79
	v_fmac_f32_e32 v17, v47, v80
	v_fmac_f32_e32 v18, v47, v81
	s_waitcnt vmcnt(34)
	v_fmac_f32_e32 v24, v47, v82
	v_fmac_f32_e32 v15, v45, v79
	v_fmac_f32_e32 v16, v45, v80
	v_fmac_f32_e32 v17, v45, v81
	v_fmac_f32_e32 v18, v45, v82
	s_waitcnt vmcnt(33)
	v_fmac_f32_e32 v24, v45, v83
	v_fmac_f32_e32 v13, v46, v79
	v_fmac_f32_e32 v15, v46, v80
	v_fmac_f32_e32 v16, v46, v81
	v_fmac_f32_e32 v17, v46, v82
	v_fmac_f32_e32 v18, v46, v83
	s_waitcnt vmcnt(32)
	v_fmac_f32_e32 v24, v46, v84
	v_fmac_f32_e32 v12, v44, v79
	v_fmac_f32_e32 v13, v44, v80
	v_fmac_f32_e32 v15, v44, v81
	v_fmac_f32_e32 v16, v44, v82
	v_fmac_f32_e32 v17, v44, v83
	v_fmac_f32_e32 v18, v44, v84
	s_waitcnt vmcnt(31)
	v_fmac_f32_e32 v24, v44, v85
	v_fmac_f32_e32 v11, v43, v79
	v_fmac_f32_e32 v12, v43, v80
	v_fmac_f32_e32 v13, v43, v81
	v_fmac_f32_e32 v15, v43, v82
	v_fmac_f32_e32 v16, v43, v83
	v_fmac_f32_e32 v17, v43, v84
	v_fmac_f32_e32 v18, v43, v85
	s_waitcnt vmcnt(30)
	v_fmac_f32_e32 v24, v43, v86
	v_fmac_f32_e32 v11, v42, v80
	v_fmac_f32_e32 v12, v42, v81
	v_fmac_f32_e32 v13, v42, v82
	v_fmac_f32_e32 v15, v42, v83
	v_fmac_f32_e32 v16, v42, v84
	v_fmac_f32_e32 v17, v42, v85
	v_fmac_f32_e32 v18, v42, v86
	s_waitcnt vmcnt(29)
	v_fmac_f32_e32 v24, v42, v87
	v_fmac_f32_e32 v11, v41, v81
	v_fmac_f32_e32 v12, v41, v82
	v_fmac_f32_e32 v13, v41, v83
	v_fmac_f32_e32 v15, v41, v84
	v_fmac_f32_e32 v16, v41, v85
	v_fmac_f32_e32 v17, v41, v86
	v_fmac_f32_e32 v18, v41, v87
	s_waitcnt vmcnt(28)
	v_fmac_f32_e32 v24, v41, v88
	v_fmac_f32_e32 v11, v40, v82
	v_fmac_f32_e32 v12, v40, v83
	v_fmac_f32_e32 v13, v40, v84
	v_fmac_f32_e32 v15, v40, v85
	v_fmac_f32_e32 v16, v40, v86
	v_fmac_f32_e32 v17, v40, v87
	v_fmac_f32_e32 v18, v40, v88
	s_waitcnt vmcnt(27)
	v_fmac_f32_e32 v24, v40, v89
	v_fmac_f32_e32 v11, v39, v83
	v_fmac_f32_e32 v12, v39, v84
	v_fmac_f32_e32 v13, v39, v85
	v_fmac_f32_e32 v15, v39, v86
	v_fmac_f32_e32 v16, v39, v87
	v_fmac_f32_e32 v17, v39, v88
	v_fmac_f32_e32 v18, v39, v89
	s_waitcnt vmcnt(26)
	v_fmac_f32_e32 v24, v39, v90
	v_fmac_f32_e32 v11, v26, v84
	v_fmac_f32_e32 v12, v26, v85
	v_fmac_f32_e32 v13, v26, v86
	v_fmac_f32_e32 v15, v26, v87
	v_fmac_f32_e32 v16, v26, v88
	v_fmac_f32_e32 v17, v26, v89
	v_fmac_f32_e32 v18, v26, v90
	s_waitcnt vmcnt(25)
	v_fmac_f32_e32 v24, v26, v64
	v_fmac_f32_e32 v11, v27, v85
	v_fmac_f32_e32 v12, v27, v86
	v_fmac_f32_e32 v13, v27, v87
	v_fmac_f32_e32 v15, v27, v88
	v_fmac_f32_e32 v16, v27, v89
	v_fmac_f32_e32 v17, v27, v90
	v_fmac_f32_e32 v18, v27, v64
	s_waitcnt vmcnt(24)
	v_fmac_f32_e32 v24, v27, v62
	s_waitcnt vmcnt(22)
	v_lshlrev_b32_e32 v27, 16, v59
	v_mul_f32_e32 v27, 0xbfb8aa3b, v27
	v_exp_f32_e32 v27, v27
	v_lshlrev_b32_e32 v26, 16, v63
	v_fmac_f32_e32 v11, v25, v86
	v_fmac_f32_e32 v12, v25, v87
	v_add_f32_e32 v27, 1.0, v27
	v_rcp_f32_e32 v27, v27
	v_fmac_f32_e32 v11, v23, v87
	v_fmac_f32_e32 v12, v23, v88
	v_fmac_f32_e32 v13, v25, v88
	v_mul_f32_e32 v39, v27, v26
	v_lshl_add_u64 v[26:27], s[66:67], 0, v[2:3]
	global_store_dword v[26:27], v39, off
	s_waitcnt vmcnt(21)
	v_lshlrev_b32_e32 v26, 16, v53
	v_mul_f32_e32 v26, 0xbfb8aa3b, v26
	v_exp_f32_e32 v26, v26
	v_fmac_f32_e32 v11, v14, v88
	v_fmac_f32_e32 v12, v14, v89
	v_fmac_f32_e32 v13, v23, v89
	v_add_f32_e32 v26, 1.0, v26
	v_fmac_f32_e32 v15, v25, v89
	v_rcp_f32_e32 v26, v26
	v_fmac_f32_e32 v11, v10, v89
	v_fmac_f32_e32 v12, v10, v90
	v_fmac_f32_e32 v13, v14, v90
	v_fmac_f32_e32 v15, v23, v90
	v_fmac_f32_e32 v16, v25, v90
	v_lshl_add_u64 v[60:61], s[38:39], 0, v[2:3]
	v_lshl_add_u64 v[48:49], s[44:45], 0, v[2:3]
	v_lshl_add_u64 v[40:41], s[60:61], 0, v[2:3]
	v_fmac_f32_e32 v11, v9, v90
	v_fmac_f32_e32 v12, v9, v64
	v_fmac_f32_e32 v13, v10, v64
	v_fmac_f32_e32 v15, v14, v64
	v_fmac_f32_e32 v16, v23, v64
	v_fmac_f32_e32 v17, v25, v64
	global_store_dword v[60:61], v79, off
	v_lshl_add_u64 v[60:61], s[40:41], 0, v[2:3]
	global_store_dword v[48:49], v82, off
	v_lshl_add_u64 v[48:49], s[46:47], 0, v[2:3]
	v_lshl_add_u64 v[44:45], s[52:53], 0, v[2:3]
	v_lshl_add_u64 v[42:43], s[56:57], 0, v[2:3]
	global_store_dword v[40:41], v90, off
	v_lshl_add_u64 v[40:41], s[62:63], 0, v[2:3]
	v_fmac_f32_e32 v11, v8, v64
	v_fmac_f32_e32 v12, v8, v62
	v_fmac_f32_e32 v13, v9, v62
	v_fmac_f32_e32 v15, v10, v62
	v_fmac_f32_e32 v16, v14, v62
	v_fmac_f32_e32 v17, v23, v62
	v_fmac_f32_e32 v18, v25, v62
	v_fmac_f32_e32 v24, v25, v39
	v_lshlrev_b32_e32 v25, 16, v55
	global_store_dword v[60:61], v80, off
	v_lshl_add_u64 v[60:61], s[42:43], 0, v[2:3]
	global_store_dword v[48:49], v83, off
	v_lshl_add_u64 v[48:49], s[48:49], 0, v[2:3]
	v_lshl_add_u64 v[46:47], s[50:51], 0, v[2:3]
	global_store_dword v[44:45], v86, off
	v_lshl_add_u64 v[44:45], s[54:55], 0, v[2:3]
	global_store_dword v[42:43], v88, off
	v_lshl_add_u64 v[42:43], s[58:59], 0, v[2:3]
	global_store_dword v[40:41], v64, off
	v_lshl_add_u64 v[40:41], s[64:65], 0, v[2:3]
	v_fmac_f32_e32 v11, v7, v62
	v_fmac_f32_e32 v12, v7, v39
	v_fmac_f32_e32 v13, v8, v39
	v_fmac_f32_e32 v15, v9, v39
	v_fmac_f32_e32 v16, v10, v39
	v_fmac_f32_e32 v17, v14, v39
	v_fmac_f32_e32 v18, v23, v39
	v_mul_f32_e32 v25, v26, v25
	v_lshl_add_u64 v[26:27], s[70:71], 0, v[2:3]
	global_store_dword v[60:61], v81, off
	global_store_dword v[48:49], v84, off
	global_store_dword v[46:47], v85, off
	global_store_dword v[44:45], v87, off
	global_store_dword v[42:43], v89, off
	global_store_dword v[40:41], v62, off
	v_fmac_f32_e32 v11, v6, v39
	global_store_dword v[26:27], v25, off
	v_fmac_f32_e32 v12, v6, v25
	v_fmac_f32_e32 v13, v7, v25
	v_fmac_f32_e32 v15, v8, v25
	v_fmac_f32_e32 v16, v9, v25
	v_fmac_f32_e32 v17, v10, v25
	v_fmac_f32_e32 v18, v14, v25
	v_fmac_f32_e32 v24, v23, v25
	s_waitcnt vmcnt(26)
	v_lshlrev_b32_e32 v25, 16, v66
	v_mul_f32_e32 v25, 0xbfb8aa3b, v25
	v_exp_f32_e32 v25, v25
	v_lshlrev_b32_e32 v23, 16, v65
	v_lshl_add_u64 v[26:27], s[74:75], 0, v[2:3]
	s_waitcnt vmcnt(16)
	v_lshlrev_b32_e32 v4, 16, v4
	v_add_f32_e32 v25, 1.0, v25
	v_rcp_f32_e32 v25, v25
	v_mul_f32_e32 v4, 0xbfb8aa3b, v4
	v_exp_f32_e32 v4, v4
	v_lshlrev_b32_e32 v5, 16, v5
	v_mul_f32_e32 v23, v25, v23
	global_store_dword v[26:27], v23, off
	v_fmac_f32_e32 v13, v6, v23
	v_fmac_f32_e32 v15, v7, v23
	v_fmac_f32_e32 v16, v8, v23
	v_fmac_f32_e32 v17, v9, v23
	v_fmac_f32_e32 v18, v10, v23
	v_fmac_f32_e32 v24, v14, v23
	v_lshlrev_b32_e32 v23, 16, v68
	v_mul_f32_e32 v23, 0xbfb8aa3b, v23
	v_exp_f32_e32 v23, v23
	v_lshlrev_b32_e32 v14, 16, v67
	v_lshl_add_u64 v[26:27], s[76:77], 0, v[2:3]
	v_add_f32_e32 v4, 1.0, v4
	v_add_f32_e32 v23, 1.0, v23
	v_rcp_f32_e32 v23, v23
	v_rcp_f32_e32 v4, v4
	v_mul_f32_e32 v14, v23, v14
	global_store_dword v[26:27], v14, off
	v_fmac_f32_e32 v15, v6, v14
	v_fmac_f32_e32 v16, v7, v14
	v_fmac_f32_e32 v17, v8, v14
	v_fmac_f32_e32 v18, v9, v14
	v_fmac_f32_e32 v24, v10, v14
	v_lshlrev_b32_e32 v14, 16, v57
	v_mul_f32_e32 v14, 0xbfb8aa3b, v14
	v_exp_f32_e32 v14, v14
	v_lshlrev_b32_e32 v10, 16, v58
	v_lshl_add_u64 v[26:27], s[78:79], 0, v[2:3]
	v_add_f32_e32 v14, 1.0, v14
	v_rcp_f32_e32 v14, v14
	s_nop 0
	v_mul_f32_e32 v10, v14, v10
	global_store_dword v[26:27], v10, off
	v_fmac_f32_e32 v16, v6, v10
	v_fmac_f32_e32 v17, v7, v10
	v_fmac_f32_e32 v18, v8, v10
	v_fmac_f32_e32 v24, v9, v10
	v_lshlrev_b32_e32 v10, 16, v54
	v_mul_f32_e32 v10, 0xbfb8aa3b, v10
	v_exp_f32_e32 v10, v10
	v_lshlrev_b32_e32 v9, 16, v56
	v_lshl_add_u64 v[26:27], s[80:81], 0, v[2:3]
	v_add_f32_e32 v10, 1.0, v10
	v_rcp_f32_e32 v10, v10
	s_nop 0
	v_mul_f32_e32 v9, v10, v9
	global_store_dword v[26:27], v9, off
	v_fmac_f32_e32 v17, v6, v9
	v_fmac_f32_e32 v18, v7, v9
	v_fmac_f32_e32 v24, v8, v9
	v_lshlrev_b32_e32 v9, 16, v51
	v_mul_f32_e32 v9, 0xbfb8aa3b, v9
	v_exp_f32_e32 v9, v9
	v_lshlrev_b32_e32 v8, 16, v52
	v_add_f32_e32 v9, 1.0, v9
	v_rcp_f32_e32 v9, v9
	s_nop 0
	v_mul_f32_e32 v10, v9, v8
	v_lshl_add_u64 v[8:9], s[82:83], 0, v[2:3]
	v_fmac_f32_e32 v24, v7, v10
	v_mul_f32_e32 v7, v4, v5
	v_lshl_add_u64 v[4:5], s[84:85], 0, v[2:3]
	global_store_dword v[8:9], v10, off
	v_fmac_f32_e32 v18, v6, v10
	global_store_dword v[4:5], v7, off
	v_fmac_f32_e32 v24, v6, v7
	v_lshl_add_u64 v[2:3], s[88:89], 0, v[2:3]
	global_load_dword v2, v[2:3], off
	v_lshl_add_u32 v3, s4, 2, v178
	s_movk_i32 s4, 0x100
	s_mov_b64 s[92:93], 0
	s_and_b64 vcc, exec, s[6:7]
	s_waitcnt vmcnt(0) lgkmcnt(0)
	v_add_f32_e32 v4, v11, v2
	v_add_f32_e32 v5, v12, v2
	v_add_f32_e32 v6, v13, v2
	v_add_f32_e32 v7, v15, v2
	v_add_f32_e32 v8, v16, v2
	v_add_f32_e32 v9, v17, v2
	v_add_f32_e32 v10, v18, v2
	v_add_f32_e32 v2, v24, v2
	ds_write2st64_b32 v3, v4, v5 offset1:8
	ds_write2st64_b32 v3, v6, v7 offset0:16 offset1:24
	ds_write2st64_b32 v3, v8, v9 offset0:32 offset1:40
	ds_write2st64_b32 v3, v10, v2 offset0:48 offset1:56
	s_cbranch_vccz .LBB0_519
	s_waitcnt lgkmcnt(0)
	s_barrier
	s_mov_b64 s[0:1], exec
	v_readlane_b32 s2, v236, 13
	v_readlane_b32 s3, v236, 14
	s_and_b64 s[2:3], s[0:1], s[2:3]
	s_mov_b64 exec, s[2:3]
	s_cbranch_execz .LBB0_517
	v_cmp_lt_i32_e32 vcc, v32, v31
	v_mov_b32_e32 v23, v19
	v_lshl_add_u64 v[24:25], s[10:11], 0, v[22:23]
	v_cndmask_b32_e32 v2, v30, v32, vcc
	v_cmp_lt_i32_e32 vcc, v33, v31
	v_lshlrev_b32_e32 v18, 2, v2
	v_lshl_add_u64 v[26:27], s[8:9], 0, v[22:23]
	v_cndmask_b32_e32 v2, v30, v33, vcc
	v_cmp_lt_i32_e32 vcc, v34, v31
	v_lshlrev_b32_e32 v39, 2, v2
	s_mov_b64 s[2:3], 0
	v_cndmask_b32_e32 v2, v30, v34, vcc
	v_cmp_lt_i32_e32 vcc, v35, v31
	v_lshlrev_b32_e32 v40, 2, v2
	v_mov_b32_e32 v23, v28
	v_cndmask_b32_e32 v2, v30, v35, vcc
	v_cmp_lt_i32_e32 vcc, v36, v31
	v_lshlrev_b32_e32 v41, 2, v2
	v_mov_b32_e32 v44, v29
	v_cndmask_b32_e32 v2, v30, v36, vcc
	v_cmp_lt_i32_e32 vcc, v37, v31
	v_lshlrev_b32_e32 v42, 2, v2
	s_nop 0
	v_cndmask_b32_e32 v2, v30, v37, vcc
	v_lshlrev_b32_e32 v43, 2, v2
